# v17 + GEMM epilogue 8-lane sums (head norm, latent ssq): ds_bpermute round trips replaced by DPP moves (quad_perm / row_half_mirror)
# speedup vs baseline: 1.0041x; 1.0041x over previous
.LBB0_373:
	s_andn2_b64 vcc, exec, s[0:1]
	s_cbranch_vccnz .LBB0_379
	s_waitcnt lgkmcnt(1)
	v_mul_f32_e32 v0, v7, v7
	v_fmac_f32_e32 v0, v6, v6
	v_fmac_f32_e32 v0, v8, v8
	v_fmac_f32_e32 v0, v9, v9
	s_waitcnt lgkmcnt(0)
	v_fmac_f32_e32 v0, v2, v2
	v_fmac_f32_e32 v0, v3, v3
	v_cmp_lt_i32_e32 vcc, v214, v215
	v_fmac_f32_e32 v0, v4, v4
	v_fmac_f32_e32 v0, v5, v5
	s_nop 1
	v_mov_b32_dpp v11, v0 quad_perm:[1,0,3,2] row_mask:0xf bank_mask:0xf
	v_cmp_lt_i32_e32 vcc, v216, v215
	s_waitcnt lgkmcnt(0)
	v_add_f32_e32 v0, v0, v11
	s_nop 1
	v_mov_b32_dpp v11, v0 quad_perm:[2,3,0,1] row_mask:0xf bank_mask:0xf
	v_cmp_lt_i32_e32 vcc, v217, v215
	s_waitcnt lgkmcnt(0)
	v_add_f32_e32 v0, v0, v11
	v_cndmask_b32_e32 v11, v213, v217, vcc
	v_lshlrev_b32_e32 v11, 2, v11
	s_nop 1
	v_mov_b32_dpp v26, v0 row_half_mirror row_mask:0xf bank_mask:0xf
	v_ashrrev_i32_e32 v11, 31, v10
	s_and_saveexec_b64 s[0:1], s[4:5]
	s_cbranch_execz .LBB0_376
	s_waitcnt lgkmcnt(0)
	v_add_f32_e32 v0, v0, v26
	v_lshlrev_b64 v[26:27], 6, v[10:11]
	v_lshl_add_u64 v[26:27], s[14:15], 0, v[26:27]
	v_lshl_add_u64 v[26:27], v[22:23], 2, v[26:27]
	global_store_dword v[26:27], v0, off offset:32

.LBB0_380:
	s_andn2_b64 vcc, exec, s[0:1]
	s_cbranch_vccnz .LBB0_384
	s_waitcnt lgkmcnt(1)
	v_mul_f32_e32 v0, v7, v7
	v_fmac_f32_e32 v0, v6, v6
	v_fmac_f32_e32 v0, v8, v8
	v_fmac_f32_e32 v0, v9, v9
	s_waitcnt lgkmcnt(0)
	v_fmac_f32_e32 v0, v2, v2
	v_fmac_f32_e32 v0, v3, v3
	v_cmp_lt_i32_e32 vcc, v214, v215
	v_fmac_f32_e32 v0, v4, v4
	v_fmac_f32_e32 v0, v5, v5
	s_nop 1
	v_mov_b32_dpp v11, v0 quad_perm:[1,0,3,2] row_mask:0xf bank_mask:0xf
	v_cmp_lt_i32_e32 vcc, v216, v215
	s_waitcnt lgkmcnt(0)
	v_add_f32_e32 v0, v0, v11
	s_nop 1
	v_mov_b32_dpp v11, v0 quad_perm:[2,3,0,1] row_mask:0xf bank_mask:0xf
	v_cmp_lt_i32_e32 vcc, v217, v215
	s_waitcnt lgkmcnt(0)
	v_add_f32_e32 v0, v0, v11
	v_cndmask_b32_e32 v11, v213, v217, vcc
	v_lshlrev_b32_e32 v11, 2, v11
	s_nop 1
	v_mov_b32_dpp v26, v0 row_half_mirror row_mask:0xf bank_mask:0xf
	v_ashrrev_i32_e32 v11, 31, v10
	s_and_saveexec_b64 s[0:1], s[4:5]
	s_cbranch_execz .LBB0_383
	s_waitcnt lgkmcnt(0)
	v_add_f32_e32 v0, v0, v26
	v_lshlrev_b64 v[26:27], 6, v[10:11]
	v_lshl_add_u64 v[26:27], v[16:17], 0, v[26:27]
	global_store_dword v[26:27], v0, off

.LBB0_417:
	s_andn2_b64 vcc, exec, s[0:1]
	s_cbranch_vccnz .LBB0_423
	s_waitcnt lgkmcnt(1)
	v_mul_f32_e32 v0, v7, v7
	v_fmac_f32_e32 v0, v6, v6
	v_fmac_f32_e32 v0, v8, v8
	v_fmac_f32_e32 v0, v9, v9
	s_waitcnt lgkmcnt(0)
	v_fmac_f32_e32 v0, v2, v2
	v_fmac_f32_e32 v0, v3, v3
	v_cmp_lt_i32_e32 vcc, v214, v215
	v_fmac_f32_e32 v0, v4, v4
	v_fmac_f32_e32 v0, v5, v5
	s_nop 1
	v_mov_b32_dpp v11, v0 quad_perm:[1,0,3,2] row_mask:0xf bank_mask:0xf
	v_cmp_lt_i32_e32 vcc, v216, v215
	v_ashrrev_i32_e32 v27, 31, v26
	s_waitcnt lgkmcnt(0)
	v_add_f32_e32 v0, v0, v11
	s_nop 1
	v_mov_b32_dpp v11, v0 quad_perm:[2,3,0,1] row_mask:0xf bank_mask:0xf
	v_cmp_lt_i32_e32 vcc, v217, v215
	s_waitcnt lgkmcnt(0)
	v_add_f32_e32 v0, v0, v11
	s_nop 1
	v_mov_b32_dpp v11, v0 row_half_mirror row_mask:0xf bank_mask:0xf
	s_and_saveexec_b64 s[0:1], s[4:5]
	s_cbranch_execz .LBB0_420
	v_lshlrev_b64 v[28:29], 6, v[26:27]
	v_lshl_add_u64 v[28:29], s[14:15], 0, v[28:29]
	s_waitcnt lgkmcnt(0)
	v_add_f32_e32 v0, v0, v11
	v_lshl_add_u64 v[28:29], v[22:23], 2, v[28:29]
	global_store_dword v[28:29], v0, off offset:32

.LBB0_424:
	s_andn2_b64 vcc, exec, s[0:1]
	s_cbranch_vccnz .LBB0_428
	s_waitcnt lgkmcnt(1)
	v_mul_f32_e32 v0, v7, v7
	v_fmac_f32_e32 v0, v6, v6
	v_fmac_f32_e32 v0, v8, v8
	v_fmac_f32_e32 v0, v9, v9
	s_waitcnt lgkmcnt(0)
	v_fmac_f32_e32 v0, v2, v2
	v_fmac_f32_e32 v0, v3, v3
	v_cmp_lt_i32_e32 vcc, v214, v215
	v_fmac_f32_e32 v0, v4, v4
	v_fmac_f32_e32 v0, v5, v5
	s_nop 1
	v_mov_b32_dpp v11, v0 quad_perm:[1,0,3,2] row_mask:0xf bank_mask:0xf
	v_cmp_lt_i32_e32 vcc, v216, v215
	v_ashrrev_i32_e32 v27, 31, v26
	s_waitcnt lgkmcnt(0)
	v_add_f32_e32 v0, v0, v11
	s_nop 1
	v_mov_b32_dpp v11, v0 quad_perm:[2,3,0,1] row_mask:0xf bank_mask:0xf
	v_cmp_lt_i32_e32 vcc, v217, v215
	s_waitcnt lgkmcnt(0)
	v_add_f32_e32 v0, v0, v11
	s_nop 1
	v_mov_b32_dpp v11, v0 row_half_mirror row_mask:0xf bank_mask:0xf
	s_and_saveexec_b64 s[0:1], s[4:5]
	s_cbranch_execz .LBB0_427
	v_lshlrev_b64 v[28:29], 6, v[26:27]
	s_waitcnt lgkmcnt(0)
	v_add_f32_e32 v0, v0, v11
	v_lshl_add_u64 v[28:29], v[16:17], 0, v[28:29]
	global_store_dword v[28:29], v0, off

.LBB0_681:
	s_andn2_b64 vcc, exec, s[0:1]
	s_cbranch_vccnz .LBB0_687
	s_waitcnt lgkmcnt(1)
	v_mul_f32_e32 v0, v7, v7
	v_fmac_f32_e32 v0, v6, v6
	v_fmac_f32_e32 v0, v8, v8
	v_fmac_f32_e32 v0, v9, v9
	s_waitcnt lgkmcnt(0)
	v_fmac_f32_e32 v0, v2, v2
	v_fmac_f32_e32 v0, v3, v3
	v_cmp_lt_i32_e32 vcc, v214, v215
	v_fmac_f32_e32 v0, v4, v4
	v_fmac_f32_e32 v0, v5, v5
	s_nop 1
	v_mov_b32_dpp v11, v0 quad_perm:[1,0,3,2] row_mask:0xf bank_mask:0xf
	v_cmp_lt_i32_e32 vcc, v216, v215
	v_ashrrev_i32_e32 v27, 31, v26
	s_waitcnt lgkmcnt(0)
	v_add_f32_e32 v0, v0, v11
	s_nop 1
	v_mov_b32_dpp v11, v0 quad_perm:[2,3,0,1] row_mask:0xf bank_mask:0xf
	v_cmp_lt_i32_e32 vcc, v217, v215
	s_waitcnt lgkmcnt(0)
	v_add_f32_e32 v0, v0, v11
	s_nop 1
	v_mov_b32_dpp v11, v0 row_half_mirror row_mask:0xf bank_mask:0xf
	s_and_saveexec_b64 s[0:1], s[4:5]
	s_cbranch_execz .LBB0_684
	v_lshlrev_b64 v[28:29], 6, v[26:27]
	v_lshl_add_u64 v[28:29], s[14:15], 0, v[28:29]
	s_waitcnt lgkmcnt(0)
	v_add_f32_e32 v0, v0, v11
	v_lshl_add_u64 v[22:23], v[22:23], 2, v[28:29]
	global_store_dword v[22:23], v0, off offset:32

.LBB0_688:
	s_andn2_b64 vcc, exec, s[0:1]
	s_cbranch_vccnz .LBB0_692
	s_waitcnt lgkmcnt(1)
	v_mul_f32_e32 v0, v7, v7
	v_fmac_f32_e32 v0, v6, v6
	v_fmac_f32_e32 v0, v8, v8
	v_fmac_f32_e32 v0, v9, v9
	s_waitcnt lgkmcnt(0)
	v_fmac_f32_e32 v0, v2, v2
	v_fmac_f32_e32 v0, v3, v3
	v_cmp_lt_i32_e32 vcc, v214, v215
	v_fmac_f32_e32 v0, v4, v4
	v_fmac_f32_e32 v0, v5, v5
	s_nop 1
	v_mov_b32_dpp v11, v0 quad_perm:[1,0,3,2] row_mask:0xf bank_mask:0xf
	v_cmp_lt_i32_e32 vcc, v216, v215
	v_ashrrev_i32_e32 v27, 31, v26
	s_waitcnt lgkmcnt(0)
	v_add_f32_e32 v0, v0, v11
	s_nop 1
	v_mov_b32_dpp v11, v0 quad_perm:[2,3,0,1] row_mask:0xf bank_mask:0xf
	v_cmp_lt_i32_e32 vcc, v217, v215
	s_waitcnt lgkmcnt(0)
	v_add_f32_e32 v0, v0, v11
	s_nop 1
	v_mov_b32_dpp v11, v0 row_half_mirror row_mask:0xf bank_mask:0xf
	s_and_saveexec_b64 s[0:1], s[4:5]
	s_cbranch_execz .LBB0_691
	v_lshlrev_b64 v[18:19], 6, v[26:27]
	s_waitcnt lgkmcnt(0)
	v_add_f32_e32 v0, v0, v11
	v_lshl_add_u64 v[16:17], v[16:17], 0, v[18:19]
	global_store_dword v[16:17], v0, off

.LBB0_929:
	s_andn2_b64 vcc, exec, s[0:1]
	v_lshl_add_u64 v[28:29], s[14:15], 0, v[10:11]
	s_cbranch_vccnz .LBB0_942
	v_cmp_lt_i32_e64 s[0:1], s43, v42
	v_cmp_gt_i32_e32 vcc, s80, v42
	s_and_saveexec_b64 s[4:5], vcc
	s_xor_b64 s[4:5], exec, s[4:5]
	v_and_b32_e32 v10, 0xff, v42
	s_or_saveexec_b64 s[4:5], s[4:5]
	v_mov_b32_e32 v44, v42
	s_xor_b64 exec, exec, s[4:5]
	v_add_u32_e32 v10, 0xffffe000, v42
	v_lshrrev_b32_e32 v11, 12, v10
	v_and_b32_e32 v10, 0xfff, v42
	v_mul_u32_u24_e32 v11, 0x1200, v11
	s_movk_i32 s34, 0x2200
	v_add3_u32 v44, v10, v11, s34
	s_or_b64 exec, exec, s[4:5]
	v_lshrrev_b32_e32 v196, 6, v10
	v_and_b32_e32 v197, 63, v10
	v_cndmask_b32_e64 v197, v197, v196, s[38:39]
	v_lshlrev_b32_e32 v196, 2, v115
	v_lshl_or_b32 v198, v197, 6, v196
	global_load_dwordx4 v[180:183], v198, s[10:11] offset:16
	global_load_dwordx4 v[184:187], v198, s[10:11]
	global_load_dwordx4 v[188:191], v198, s[12:13] offset:16
	global_load_dwordx4 v[192:195], v198, s[12:13]
	s_waitcnt lgkmcnt(1)
	v_pk_mul_f32 v[14:15], v[2:3], v[2:3]
	v_pk_mul_f32 v[12:13], v[4:5], v[4:5]
	v_add_f32_e32 v11, v14, v15
	v_add_f32_e32 v11, v12, v11
	s_waitcnt lgkmcnt(0)
	v_pk_mul_f32 v[18:19], v[6:7], v[6:7]
	v_add_f32_e32 v11, v13, v11
	v_add_f32_e32 v11, v18, v11
	v_pk_mul_f32 v[16:17], v[8:9], v[8:9]
	v_add_f32_e32 v11, v19, v11
	v_cmp_lt_i32_e32 vcc, v214, v215
	v_add_f32_e32 v11, v16, v11
	v_add_f32_e32 v11, v17, v11
	s_nop 1
	v_mov_b32_dpp v12, v11 quad_perm:[1,0,3,2] row_mask:0xf bank_mask:0xf
	v_cmp_lt_i32_e32 vcc, v216, v215
	s_nor_b64 s[34:35], s[20:21], s[0:1]
	v_ashrrev_i32_e32 v43, 31, v42
	s_waitcnt lgkmcnt(0)
	v_add_f32_e32 v11, v11, v12
	s_nop 1
	v_mov_b32_dpp v12, v11 quad_perm:[2,3,0,1] row_mask:0xf bank_mask:0xf
	v_cmp_lt_i32_e32 vcc, v217, v215
	s_waitcnt lgkmcnt(0)
	v_add_f32_e32 v11, v11, v12
	s_nop 1
	v_mov_b32_dpp v12, v11 row_half_mirror row_mask:0xf bank_mask:0xf
	s_waitcnt lgkmcnt(0)
	v_add_f32_e32 v11, v11, v12
	v_fmamk_f32 v11, v11, 0x3c800000, v207
	v_mul_f32_e32 v12, 0x4b800000, v11
	v_cmp_gt_f32_e32 vcc, s42, v11
	s_nop 1
	v_cndmask_b32_e32 v11, v11, v12, vcc
	v_rsq_f32_e32 v11, v11
	s_nop 0
	v_mul_f32_e32 v12, 0x45800000, v11
	v_cndmask_b32_e32 v46, v11, v12, vcc
	v_pk_mul_f32 v[2:3], v[2:3], v[46:47] op_sel_hi:[1,0]
	v_pk_mul_f32 v[4:5], v[4:5], v[46:47] op_sel_hi:[1,0]
	v_pk_mul_f32 v[6:7], v[6:7], v[46:47] op_sel_hi:[1,0]
	v_pk_mul_f32 v[8:9], v[8:9], v[46:47] op_sel_hi:[1,0]
	s_waitcnt vmcnt(4)
	v_pk_mul_f32 v[2:3], v[32:33], v[2:3]
	v_pk_mul_f32 v[4:5], v[34:35], v[4:5]
	v_pk_mul_f32 v[6:7], v[36:37], v[6:7]
	v_pk_mul_f32 v[8:9], v[38:39], v[8:9]
	s_and_saveexec_b64 s[4:5], s[34:35]
	s_cbranch_execz .LBB0_936
	v_readlane_b32 s34, v254, 13
	v_lshlrev_b64 v[12:13], 9, v[42:43]
	v_readlane_b32 s35, v254, 14
	s_nop 1
	v_lshl_add_u64 v[12:13], s[34:35], 0, v[12:13]
	v_lshl_add_u64 v[12:13], v[40:41], 2, v[12:13]
	v_add_co_u32_e32 v12, vcc, 0x5fff000, v12
	s_nop 1
	v_addc_co_u32_e32 v13, vcc, 0, v13, vcc
	global_store_dwordx4 v[12:13], v[2:5], off offset:2048
	global_store_dwordx4 v[12:13], v[6:9], off offset:2064

.LBB0_952:
	s_andn2_b64 vcc, exec, s[0:1]
	s_cbranch_vccnz .LBB0_965
	v_cmp_lt_i32_e64 s[0:1], s43, v42
	v_cmp_gt_i32_e32 vcc, s80, v42
	s_and_saveexec_b64 s[24:25], vcc
	s_xor_b64 s[24:25], exec, s[24:25]
	v_and_b32_e32 v10, 0xff, v42
	s_or_saveexec_b64 s[24:25], s[24:25]
	v_mov_b32_e32 v44, v42
	s_xor_b64 exec, exec, s[24:25]
	v_add_u32_e32 v10, 0xffffe000, v42
	v_lshrrev_b32_e32 v11, 12, v10
	v_and_b32_e32 v10, 0xfff, v42
	v_mul_u32_u24_e32 v11, 0x1200, v11
	s_movk_i32 s34, 0x2200
	v_add3_u32 v44, v10, v11, s34
	s_or_b64 exec, exec, s[24:25]
	v_lshrrev_b32_e32 v196, 6, v10
	v_and_b32_e32 v197, 63, v10
	v_cndmask_b32_e64 v197, v197, v196, s[38:39]
	v_lshlrev_b32_e32 v196, 2, v115
	v_lshl_or_b32 v198, v197, 6, v196
	global_load_dwordx4 v[180:183], v198, s[10:11] offset:16
	global_load_dwordx4 v[184:187], v198, s[10:11]
	global_load_dwordx4 v[188:191], v198, s[12:13] offset:16
	global_load_dwordx4 v[192:195], v198, s[12:13]
	s_waitcnt lgkmcnt(1)
	v_pk_mul_f32 v[14:15], v[2:3], v[2:3]
	v_pk_mul_f32 v[12:13], v[4:5], v[4:5]
	v_add_f32_e32 v11, v14, v15
	v_add_f32_e32 v11, v12, v11
	s_waitcnt lgkmcnt(0)
	v_pk_mul_f32 v[18:19], v[6:7], v[6:7]
	v_add_f32_e32 v11, v13, v11
	v_add_f32_e32 v11, v18, v11
	v_pk_mul_f32 v[16:17], v[8:9], v[8:9]
	v_add_f32_e32 v11, v19, v11
	v_cmp_lt_i32_e32 vcc, v214, v215
	v_add_f32_e32 v11, v16, v11
	v_add_f32_e32 v11, v17, v11
	s_nop 1
	v_mov_b32_dpp v12, v11 quad_perm:[1,0,3,2] row_mask:0xf bank_mask:0xf
	v_cmp_lt_i32_e32 vcc, v216, v215
	s_nor_b64 s[34:35], s[20:21], s[0:1]
	v_ashrrev_i32_e32 v43, 31, v42
	s_waitcnt lgkmcnt(0)
	v_add_f32_e32 v11, v11, v12
	s_nop 1
	v_mov_b32_dpp v12, v11 quad_perm:[2,3,0,1] row_mask:0xf bank_mask:0xf
	v_cmp_lt_i32_e32 vcc, v217, v215
	s_waitcnt lgkmcnt(0)
	v_add_f32_e32 v11, v11, v12
	s_nop 1
	v_mov_b32_dpp v12, v11 row_half_mirror row_mask:0xf bank_mask:0xf
	s_waitcnt lgkmcnt(0)
	v_add_f32_e32 v11, v11, v12
	v_fmamk_f32 v11, v11, 0x3c800000, v207
	v_mul_f32_e32 v12, 0x4b800000, v11
	v_cmp_gt_f32_e32 vcc, s42, v11
	s_nop 1
	v_cndmask_b32_e32 v11, v11, v12, vcc
	v_rsq_f32_e32 v11, v11
	s_nop 0
	v_mul_f32_e32 v12, 0x45800000, v11
	v_cndmask_b32_e32 v46, v11, v12, vcc
	v_pk_mul_f32 v[2:3], v[2:3], v[46:47] op_sel_hi:[1,0]
	v_pk_mul_f32 v[4:5], v[4:5], v[46:47] op_sel_hi:[1,0]
	v_pk_mul_f32 v[6:7], v[6:7], v[46:47] op_sel_hi:[1,0]
	v_pk_mul_f32 v[8:9], v[8:9], v[46:47] op_sel_hi:[1,0]
	s_waitcnt vmcnt(4)
	v_pk_mul_f32 v[2:3], v[32:33], v[2:3]
	v_pk_mul_f32 v[4:5], v[34:35], v[4:5]
	v_pk_mul_f32 v[6:7], v[36:37], v[6:7]
	v_pk_mul_f32 v[8:9], v[38:39], v[8:9]
	s_and_saveexec_b64 s[24:25], s[34:35]
	s_cbranch_execz .LBB0_959
	v_readlane_b32 s34, v254, 13
	v_lshlrev_b64 v[12:13], 9, v[42:43]
	v_readlane_b32 s35, v254, 14
	s_nop 1
	v_lshl_add_u64 v[12:13], s[34:35], 0, v[12:13]
	v_lshl_add_u64 v[12:13], v[40:41], 2, v[12:13]
	v_add_co_u32_e32 v12, vcc, 0x5fff000, v12
	s_nop 1
	v_addc_co_u32_e32 v13, vcc, 0, v13, vcc
	global_store_dwordx4 v[12:13], v[2:5], off offset:2048
	global_store_dwordx4 v[12:13], v[6:9], off offset:2064

.LBB0_1090:
	s_andn2_b64 vcc, exec, s[0:1]
	s_cbranch_vccnz .LBB0_1103
	v_cmp_lt_i32_e64 s[0:1], s43, v42
	v_cmp_gt_i32_e32 vcc, s80, v42
	s_and_saveexec_b64 s[4:5], vcc
	s_xor_b64 s[4:5], exec, s[4:5]
	v_and_b32_e32 v10, 0xff, v42
	s_or_saveexec_b64 s[4:5], s[4:5]
	v_mov_b32_e32 v44, v42
	s_xor_b64 exec, exec, s[4:5]
	v_add_u32_e32 v10, 0xffffe000, v42
	v_lshrrev_b32_e32 v11, 12, v10
	v_and_b32_e32 v10, 0xfff, v42
	v_mul_u32_u24_e32 v11, 0x1200, v11
	s_movk_i32 s6, 0x2200
	v_add3_u32 v44, v10, v11, s6
	s_or_b64 exec, exec, s[4:5]
	v_lshrrev_b32_e32 v196, 6, v10
	v_and_b32_e32 v197, 63, v10
	v_cndmask_b32_e64 v197, v197, v196, s[38:39]
	v_lshlrev_b32_e32 v196, 2, v115
	v_lshl_or_b32 v198, v197, 6, v196
	global_load_dwordx4 v[180:183], v198, s[10:11] offset:16
	global_load_dwordx4 v[184:187], v198, s[10:11]
	global_load_dwordx4 v[188:191], v198, s[12:13] offset:16
	global_load_dwordx4 v[192:195], v198, s[12:13]
	s_waitcnt lgkmcnt(1)
	v_pk_mul_f32 v[14:15], v[2:3], v[2:3]
	v_pk_mul_f32 v[12:13], v[4:5], v[4:5]
	v_add_f32_e32 v11, v14, v15
	v_add_f32_e32 v11, v12, v11
	s_waitcnt lgkmcnt(0)
	v_pk_mul_f32 v[18:19], v[6:7], v[6:7]
	v_add_f32_e32 v11, v13, v11
	v_add_f32_e32 v11, v18, v11
	v_pk_mul_f32 v[16:17], v[8:9], v[8:9]
	v_add_f32_e32 v11, v19, v11
	v_cmp_lt_i32_e32 vcc, v214, v215
	v_add_f32_e32 v11, v16, v11
	v_add_f32_e32 v11, v17, v11
	s_nop 1
	v_mov_b32_dpp v12, v11 quad_perm:[1,0,3,2] row_mask:0xf bank_mask:0xf
	v_cmp_lt_i32_e32 vcc, v216, v215
	s_nor_b64 s[6:7], s[20:21], s[0:1]
	v_ashrrev_i32_e32 v43, 31, v42
	s_waitcnt lgkmcnt(0)
	v_add_f32_e32 v11, v11, v12
	s_nop 1
	v_mov_b32_dpp v12, v11 quad_perm:[2,3,0,1] row_mask:0xf bank_mask:0xf
	v_cmp_lt_i32_e32 vcc, v217, v215
	s_waitcnt lgkmcnt(0)
	v_add_f32_e32 v11, v11, v12
	s_nop 1
	v_mov_b32_dpp v12, v11 row_half_mirror row_mask:0xf bank_mask:0xf
	s_waitcnt lgkmcnt(0)
	v_add_f32_e32 v11, v11, v12
	v_fmamk_f32 v11, v11, 0x3c800000, v207
	v_mul_f32_e32 v12, 0x4b800000, v11
	v_cmp_gt_f32_e32 vcc, s42, v11
	s_nop 1
	v_cndmask_b32_e32 v11, v11, v12, vcc
	v_rsq_f32_e32 v11, v11
	s_nop 0
	v_mul_f32_e32 v12, 0x45800000, v11
	v_cndmask_b32_e32 v46, v11, v12, vcc
	v_pk_mul_f32 v[2:3], v[2:3], v[46:47] op_sel_hi:[1,0]
	v_pk_mul_f32 v[4:5], v[4:5], v[46:47] op_sel_hi:[1,0]
	v_pk_mul_f32 v[6:7], v[6:7], v[46:47] op_sel_hi:[1,0]
	v_pk_mul_f32 v[8:9], v[8:9], v[46:47] op_sel_hi:[1,0]
	s_waitcnt vmcnt(4)
	v_pk_mul_f32 v[2:3], v[32:33], v[2:3]
	v_pk_mul_f32 v[4:5], v[34:35], v[4:5]
	v_pk_mul_f32 v[6:7], v[36:37], v[6:7]
	v_pk_mul_f32 v[8:9], v[38:39], v[8:9]
	s_and_saveexec_b64 s[4:5], s[6:7]
	s_cbranch_execz .LBB0_1097
	v_readlane_b32 s6, v254, 13
	v_lshlrev_b64 v[12:13], 9, v[42:43]
	v_readlane_b32 s7, v254, 14
	s_nop 1
	v_lshl_add_u64 v[12:13], s[6:7], 0, v[12:13]
	v_lshl_add_u64 v[12:13], v[40:41], 2, v[12:13]
	v_add_co_u32_e32 v12, vcc, 0x5fff000, v12
	s_nop 1
	v_addc_co_u32_e32 v13, vcc, 0, v13, vcc
	global_store_dwordx4 v[12:13], v[2:5], off offset:2048
	global_store_dwordx4 v[12:13], v[6:9], off offset:2064
